# cross-attn tile loop: K-fragment ds_reads hoisted above the next-tile LDS stores (issued right after the tile barrier), ladders recomputed
# baseline (speedup 1.0000x reference)
; template <int D, int DV, int MODE, int NMAP, int KT> ...
;     ...
;     AT_LOAD(0);
;     __syncthreads();
;     AT_STORE(0);
;     if (nkt > 1) AT_LOAD(1);
;     for (int kt = 0; kt < nkt; ++kt) {
;         __syncthreads();
;         const int cur = (kt & 1) * BUF_BYTES;
;         if (kt + 1 < nkt) { AT_STORE(((kt + 1) & 1) * BUF_BYTES); if (kt + 2 < nkt) AT_LOAD(kt + 2); }
.LBB0_601:
	s_add_i32 s14, s15, 1
	s_bitcmp1_b32 s14, 0
	s_cselect_b32 s16, 0x11400, 0
	s_add_i32 s16, s16, 0
	v_add3_u32 v250, s16, v161, v162
	s_bitcmp1_b32 s15, 0
	s_cselect_b32 s98, 0x11400, 0
	v_add3_u32 v184, s98, v148, v170
	s_waitcnt lgkmcnt(0)
	s_barrier
	ds_read_b128 v[130:133], v184
	ds_read_b128 v[134:137], v184 offset:64
	ds_read_b128 v[138:141], v184 offset:128
	ds_read_b128 v[142:145], v184 offset:192
	ds_read_b128 v[176:179], v184 offset:256
	ds_read_b128 v[180:183], v184 offset:320
	ds_read_b128 v[194:197], v184 offset:384
	ds_read_b128 v[198:201], v184 offset:448
	ds_read_b128 v[202:205], v184 offset:8448
	ds_read_b128 v[206:209], v184 offset:8512
	ds_read_b128 v[226:229], v184 offset:8576
	ds_read_b128 v[230:233], v184 offset:8640
	ds_read_b128 v[234:237], v184 offset:8704
	ds_read_b128 v[238:241], v184 offset:8768
	ds_read_b128 v[242:245], v184 offset:8832
	ds_read_b128 v[246:249], v184 offset:8896
	s_waitcnt vmcnt(0)
	ds_write_b128 v250, v[98:101]
	v_add3_u32 v250, s16, v163, v164
	ds_write_b128 v250, v[102:105]
	v_add3_u32 v250, s16, v165, v166
	s_add_i32 s17, s16, s30
	ds_write_b128 v250, v[106:109]
	v_add3_u32 v250, s16, v167, v168
	s_add_i32 s17, s17, s31
	ds_write_b128 v250, v[110:113]
	v_add_u32_e32 v250, s17, v169
	s_add_i32 s17, s16, s33
	s_add_i32 s17, s17, s34
	ds_write_b16 v250, v114 offset:33792
	ds_write_b16_d16_hi v250, v114 offset:33936
	ds_write_b16 v250, v115 offset:34080
	ds_write_b16_d16_hi v250, v115 offset:34224
	ds_write_b16 v250, v116 offset:34368
	ds_write_b16_d16_hi v250, v116 offset:34512
	ds_write_b16 v250, v117 offset:34656
	ds_write_b16_d16_hi v250, v117 offset:34800
	v_add_u32_e32 v250, s17, v169
	s_add_i32 s17, s16, s40
	s_add_i32 s17, s17, s41
	s_add_i32 s16, s16, s42
	ds_write_b16 v250, v118 offset:33792
	ds_write_b16_d16_hi v250, v118 offset:33936
	ds_write_b16 v250, v119 offset:34080
	ds_write_b16_d16_hi v250, v119 offset:34224
	ds_write_b16 v250, v120 offset:34368
	ds_write_b16_d16_hi v250, v120 offset:34512
	ds_write_b16 v250, v121 offset:34656
	ds_write_b16_d16_hi v250, v121 offset:34800
	v_add_u32_e32 v250, s17, v169
	s_add_i32 s16, s16, s43
	ds_write_b16 v250, v122 offset:33792
	ds_write_b16_d16_hi v250, v122 offset:33936
	ds_write_b16 v250, v123 offset:34080
	ds_write_b16_d16_hi v250, v123 offset:34224
	ds_write_b16 v250, v124 offset:34368
	ds_write_b16_d16_hi v250, v124 offset:34512
	ds_write_b16 v250, v125 offset:34656
	ds_write_b16_d16_hi v250, v125 offset:34800
	v_add_u32_e32 v250, s16, v169
	s_cmp_gt_u32 s15, 1
	ds_write_b16 v250, v126 offset:33792
	ds_write_b16_d16_hi v250, v126 offset:33936
	ds_write_b16 v250, v127 offset:34080
	ds_write_b16_d16_hi v250, v127 offset:34224
	ds_write_b16 v250, v128 offset:34368
	ds_write_b16_d16_hi v250, v128 offset:34512
	ds_write_b16 v250, v129 offset:34656
	ds_write_b16_d16_hi v250, v129 offset:34800
	s_cbranch_scc1 .LBB0_603
	v_add_u32_e32 v114, s44, v174
	v_add_u32_e32 v116, s44, v173
	v_add_u32_e32 v122, s44, v172
	v_add_u32_e32 v124, s44, v171
	v_ashrrev_i32_e32 v115, 31, v114
	v_ashrrev_i32_e32 v117, 31, v116
	v_ashrrev_i32_e32 v123, 31, v122
	v_ashrrev_i32_e32 v125, 31, v124
	v_lshlrev_b64 v[114:115], 12, v[114:115]
	v_lshlrev_b64 v[116:117], 12, v[116:117]
	v_lshlrev_b64 v[122:123], 12, v[122:123]
	v_lshlrev_b64 v[124:125], 12, v[124:125]
	v_lshl_add_u64 v[98:99], v[156:157], 0, s[94:95]
	v_lshl_add_u64 v[102:103], v[154:155], 0, s[94:95]
	v_lshl_add_u64 v[106:107], v[152:153], 0, s[94:95]
	v_lshl_add_u64 v[110:111], v[150:151], 0, s[94:95]
	v_lshl_add_u64 v[114:115], s[6:7], 0, v[114:115]
	v_lshl_add_u64 v[118:119], s[8:9], 0, v[116:117]
	v_lshl_add_u64 v[122:123], s[10:11], 0, v[122:123]
	v_lshl_add_u64 v[126:127], s[12:13], 0, v[124:125]
	global_load_dwordx4 v[98:101], v[98:99], off
	s_nop 0
	global_load_dwordx4 v[102:105], v[102:103], off
	s_nop 0
	global_load_dwordx4 v[106:109], v[106:107], off
	s_nop 0
	global_load_dwordx4 v[110:113], v[110:111], off
	s_nop 0
	global_load_dwordx4 v[114:117], v[114:115], off offset:2048
	s_nop 0
	global_load_dwordx4 v[118:121], v[118:119], off offset:2048
	s_nop 0
	global_load_dwordx4 v[122:125], v[122:123], off offset:2048
	s_nop 0
	global_load_dwordx4 v[126:129], v[126:127], off offset:2048
; #define LAS __attribute__((address_space(3)))
; template <int D, int DV, int MODE, int NMAP, int KT> ...
;     ...
;         if (MODE == 0 || kt * KT <= rowmin + 15) {
;             const LAS bf16_t* Ks = (const LAS bf16_t*)(lds + cur); const LAS bf16_t* Vt = (const LAS bf16_t*)(lds + cur + KS_BYTES);
;             const bool diag = (MODE != 0) && (kt * KT + KT - 1 > rowmin);
;             bf16x8 pb[NMAP][KK2];
;             f32x4 sall[NMAP][NB];
; #pragma unroll
;             for (int mp = 0; mp < NMAP; ++mp) {
;                 f32x4 (&s)[NB] = sall[mp];
;                 constexpr int KD = D / 32, NBB = (KD >= 8) ? 1 : (8 / KD), NSB = NB / NBB;
;                 bf16x8 kfr[2][NBB][KD];
;     ...
;                 AT_SLOAD(0, 0);
; #pragma unroll
;                 for (int bi = 0; bi < NSB; ++bi) {
;                     if (bi + 1 < NSB) AT_SLOAD(bi + 1, (bi + 1) & 1);
;                     __builtin_amdgcn_sched_barrier(0);
;                     __builtin_amdgcn_s_setprio(1);
; #pragma unroll
;                     for (int x_ = 0; x_ < NBB; ++x_) { const int nb = bi * NBB + x_;
;                         s[nb] = __builtin_amdgcn_mfma_f32_16x16x32_bf16(kfr[bi & 1][x_][0], qf[mp][0], (f32x4){0.f, 0.f, 0.f, 0.f}, 0, 0, 0);
; #pragma unroll
;                         for (int kk = 1; kk < KD; ++kk) s[nb] = __builtin_amdgcn_mfma_f32_16x16x32_bf16(kfr[bi & 1][x_][kk], qf[mp][kk], s[nb], 0, 0, 0); }
;                     __builtin_amdgcn_s_setprio(0);
;                     __builtin_amdgcn_sched_barrier(0);
;                 }
;     ...
;             }
; #pragma unroll
;             for (int mp = 0; mp < NMAP; ++mp) {
;                 f32x4 (&s)[NB] = sall[mp];
;                 if (MODE < 2) {
;                     if (diag) {
; #pragma unroll
;                         for (int nb = 0; nb < NB; ++nb)
; #pragma unroll
;                             for (int j = 0; j < 4; ++j) { if (kt * KT + nb * 16 + g4 * 4 + j > myrow) s[nb][j] = -INFINITY; }
;                     }
;                     float mx = fmaxf(fmaxf(s[0][0], s[0][1]), s[0][2]);
;                     mx = fmaxf(fmaxf(mx, s[0][3]), s[1][0]); mx = fmaxf(fmaxf(mx, s[1][1]), s[1][2]); mx = fmaxf(fmaxf(mx, s[1][3]), s[2][0]);
;                     mx = fmaxf(fmaxf(mx, s[2][1]), s[2][2]); mx = fmaxf(fmaxf(mx, s[2][3]), s[3][0]); mx = fmaxf(fmaxf(mx, s[3][1]), s[3][2]); mx = fmaxf(mx, s[3][3]);
; #pragma unroll
.LBB0_603:
	s_bitcmp1_b32 s15, 0
	s_cselect_b32 s15, 0x11400, 0
	s_add_i32 s15, s15, 0
	s_setprio 1
	s_waitcnt lgkmcnt(14)
	v_mfma_f32_16x16x32_bf16 v[130:133], v[130:133], v[66:69], 0
	v_mfma_f32_16x16x32_bf16 v[130:133], v[134:137], v[70:73], v[130:133]
	v_mfma_f32_16x16x32_bf16 v[130:133], v[138:141], v[74:77], v[130:133]
	v_mfma_f32_16x16x32_bf16 v[130:133], v[142:145], v[78:81], v[130:133]
	v_mfma_f32_16x16x32_bf16 v[130:133], v[176:179], v[82:85], v[130:133]
	v_mfma_f32_16x16x32_bf16 v[130:133], v[180:183], v[86:89], v[130:133]
	v_mfma_f32_16x16x32_bf16 v[130:133], v[194:197], v[90:93], v[130:133]
	v_mfma_f32_16x16x32_bf16 v[142:145], v[198:201], v[94:97], v[130:133]
	s_setprio 0
	s_nop 5
	ds_read_b128 v[130:133], v184 offset:16896
	ds_read_b128 v[134:137], v184 offset:16960
	ds_read_b128 v[176:179], v184 offset:17024
	ds_read_b128 v[180:183], v184 offset:17088
	ds_read_b128 v[194:197], v184 offset:17152
	ds_read_b128 v[198:201], v184 offset:17216
	ds_read_b128 v[250:253], v184 offset:17280
	ds_read_b128 v[212:215], v184 offset:17344
	s_setprio 1
	v_mfma_f32_16x16x32_bf16 v[138:141], v[202:205], v[66:69], 0
	v_mfma_f32_16x16x32_bf16 v[138:141], v[206:209], v[70:73], v[138:141]
	v_mfma_f32_16x16x32_bf16 v[138:141], v[226:229], v[74:77], v[138:141]
	v_mfma_f32_16x16x32_bf16 v[138:141], v[230:233], v[78:81], v[138:141]
	v_mfma_f32_16x16x32_bf16 v[138:141], v[234:237], v[82:85], v[138:141]
	v_mfma_f32_16x16x32_bf16 v[138:141], v[238:241], v[86:89], v[138:141]
	v_mfma_f32_16x16x32_bf16 v[138:141], v[242:245], v[90:93], v[138:141]
	v_mfma_f32_16x16x32_bf16 v[138:141], v[246:249], v[94:97], v[138:141]
	s_setprio 0
	ds_read_b128 v[202:205], v184 offset:25344
	ds_read_b128 v[206:209], v184 offset:25408
	ds_read_b128 v[226:229], v184 offset:25472
	ds_read_b128 v[230:233], v184 offset:25536
	ds_read_b128 v[234:237], v184 offset:25600
	ds_read_b128 v[238:241], v184 offset:25664
	ds_read_b128 v[242:245], v184 offset:25728
	ds_read_b128 v[246:249], v184 offset:25792
	s_setprio 1
	s_waitcnt lgkmcnt(14)
	v_mfma_f32_16x16x32_bf16 v[130:133], v[130:133], v[66:69], 0
	v_mfma_f32_16x16x32_bf16 v[130:133], v[134:137], v[70:73], v[130:133]
	s_waitcnt lgkmcnt(13)
	v_mfma_f32_16x16x32_bf16 v[130:133], v[176:179], v[74:77], v[130:133]
	s_waitcnt lgkmcnt(12)
	v_mfma_f32_16x16x32_bf16 v[130:133], v[180:183], v[78:81], v[130:133]
	s_waitcnt lgkmcnt(11)
	v_mfma_f32_16x16x32_bf16 v[130:133], v[194:197], v[82:85], v[130:133]
	s_waitcnt lgkmcnt(10)
	v_mfma_f32_16x16x32_bf16 v[130:133], v[198:201], v[86:89], v[130:133]
	s_waitcnt lgkmcnt(9)
	v_mfma_f32_16x16x32_bf16 v[130:133], v[250:253], v[90:93], v[130:133]
	s_waitcnt lgkmcnt(8)
	v_mfma_f32_16x16x32_bf16 v[134:137], v[212:215], v[94:97], v[130:133]
	s_setprio 0
	s_setprio 1
	s_waitcnt lgkmcnt(7)
	v_mfma_f32_16x16x32_bf16 v[130:133], v[202:205], v[66:69], 0
	s_waitcnt lgkmcnt(6)
	v_mfma_f32_16x16x32_bf16 v[130:133], v[206:209], v[70:73], v[130:133]
	s_waitcnt lgkmcnt(5)
	v_mfma_f32_16x16x32_bf16 v[130:133], v[226:229], v[74:77], v[130:133]
	s_waitcnt lgkmcnt(4)
	v_mfma_f32_16x16x32_bf16 v[130:133], v[230:233], v[78:81], v[130:133]
	s_waitcnt lgkmcnt(3)
	v_mfma_f32_16x16x32_bf16 v[130:133], v[234:237], v[82:85], v[130:133]
	s_waitcnt lgkmcnt(2)
	v_mfma_f32_16x16x32_bf16 v[130:133], v[238:241], v[86:89], v[130:133]
	s_waitcnt lgkmcnt(1)
	v_mfma_f32_16x16x32_bf16 v[130:133], v[242:245], v[90:93], v[130:133]
	s_waitcnt lgkmcnt(0)
	v_mfma_f32_16x16x32_bf16 v[130:133], v[246:249], v[94:97], v[130:133]
	s_setprio 0
	v_max_f32_e32 v176, v143, v143
	v_max_f32_e32 v177, v142, v142
	v_max_f32_e32 v176, v177, v176
	v_max3_f32 v176, v176, v144, v145
	v_max3_f32 v176, v176, v138, v139
	v_max3_f32 v176, v176, v140, v141
	v_max3_f32 v176, v176, v134, v135
	v_max3_f32 v176, v176, v136, v137
	v_max3_f32 v176, v176, v130, v131
	v_max3_f32 v176, v176, v132, v133
	v_mov_b32_e32 v177, v176
	s_nop 1
	v_permlane16_swap_b32_e32 v176, v177
	v_max_f32_e32 v177, v177, v177
	v_max_f32_e32 v176, v176, v176
	v_max_f32_e32 v176, v176, v177
	v_mov_b32_e32 v177, v176
	s_nop 1
	v_permlane32_swap_b32_e32 v176, v177
	v_max_f32_e32 v177, v177, v177
	v_max_f32_e32 v176, v176, v176
	v_max_f32_e32 v176, v176, v177
	v_mul_f32_e32 v176, 0x3db8aa3b, v176
	v_add_f32_e32 v177, 0x40c00000, v175
	v_cmp_gt_f32_e32 vcc, v176, v177
	s_cbranch_vccz .LBB0_605
	v_max_f32_e32 v176, v176, v176
	v_max_f32_e32 v177, v175, v175
	v_max_f32_e32 v177, v177, v176
	v_sub_f32_e32 v175, v175, v177
	v_exp_f32_e32 v176, v175
	v_mov_b32_e32 v175, v177
	v_mul_f32_e32 v159, v159, v176
	v_pk_mul_f32 v[64:65], v[64:65], v[176:177] op_sel_hi:[1,0]
	v_pk_mul_f32 v[62:63], v[62:63], v[176:177] op_sel_hi:[1,0]
	v_pk_mul_f32 v[60:61], v[60:61], v[176:177] op_sel_hi:[1,0]
	v_pk_mul_f32 v[58:59], v[58:59], v[176:177] op_sel_hi:[1,0]
	v_pk_mul_f32 v[56:57], v[56:57], v[176:177] op_sel_hi:[1,0]
	v_pk_mul_f32 v[54:55], v[54:55], v[176:177] op_sel_hi:[1,0]
	v_pk_mul_f32 v[52:53], v[52:53], v[176:177] op_sel_hi:[1,0]
	v_pk_mul_f32 v[50:51], v[50:51], v[176:177] op_sel_hi:[1,0]
	v_pk_mul_f32 v[48:49], v[48:49], v[176:177] op_sel_hi:[1,0]
	v_pk_mul_f32 v[46:47], v[46:47], v[176:177] op_sel_hi:[1,0]
	v_pk_mul_f32 v[44:45], v[44:45], v[176:177] op_sel_hi:[1,0]
	v_pk_mul_f32 v[42:43], v[42:43], v[176:177] op_sel_hi:[1,0]
	v_pk_mul_f32 v[40:41], v[40:41], v[176:177] op_sel_hi:[1,0]
	v_pk_mul_f32 v[38:39], v[38:39], v[176:177] op_sel_hi:[1,0]
	v_pk_mul_f32 v[36:37], v[36:37], v[176:177] op_sel_hi:[1,0]
	v_pk_mul_f32 v[34:35], v[34:35], v[176:177] op_sel_hi:[1,0]
	v_pk_mul_f32 v[32:33], v[32:33], v[176:177] op_sel_hi:[1,0]
	v_pk_mul_f32 v[30:31], v[30:31], v[176:177] op_sel_hi:[1,0]
	v_pk_mul_f32 v[28:29], v[28:29], v[176:177] op_sel_hi:[1,0]
	v_pk_mul_f32 v[26:27], v[26:27], v[176:177] op_sel_hi:[1,0]
	v_pk_mul_f32 v[24:25], v[24:25], v[176:177] op_sel_hi:[1,0]
	v_pk_mul_f32 v[22:23], v[22:23], v[176:177] op_sel_hi:[1,0]
	v_pk_mul_f32 v[20:21], v[20:21], v[176:177] op_sel_hi:[1,0]
	v_pk_mul_f32 v[18:19], v[18:19], v[176:177] op_sel_hi:[1,0]
	v_pk_mul_f32 v[16:17], v[16:17], v[176:177] op_sel_hi:[1,0]
	v_pk_mul_f32 v[14:15], v[14:15], v[176:177] op_sel_hi:[1,0]
	v_pk_mul_f32 v[12:13], v[12:13], v[176:177] op_sel_hi:[1,0]
	v_pk_mul_f32 v[10:11], v[10:11], v[176:177] op_sel_hi:[1,0]
	v_pk_mul_f32 v[8:9], v[8:9], v[176:177] op_sel_hi:[1,0]
	v_pk_mul_f32 v[6:7], v[6:7], v[176:177] op_sel_hi:[1,0]
	v_pk_mul_f32 v[4:5], v[4:5], v[176:177] op_sel_hi:[1,0]
	v_pk_mul_f32 v[2:3], v[2:3], v[176:177] op_sel_hi:[1,0]
